# v10 + attention block loop trimmed: precomputed LDS row bases, hoisted bpermute lane addresses, 18-op row-max tree
# speedup vs baseline: 1.0016x; 1.0016x over previous
.LBB0_309:
	v_readlane_b32 s4, v255, 11
	v_readlane_b32 s5, v255, 12
	s_andn2_b64 vcc, exec, s[4:5]
	s_cbranch_vccnz .LBB0_329
	v_writelane_b32 v255, s44, 58
	s_waitcnt lgkmcnt(0)
	s_add_u32 s3, s0, 0x9900000
	v_bfe_u32 v3, v0, 4, 2
	v_writelane_b32 v255, s45, 59
	v_writelane_b32 v255, s56, 60
	v_lshlrev_b32_e32 v7, 2, v3
	v_and_b32_e32 v1, 15, v0
	v_writelane_b32 v255, s57, 61
	v_writelane_b32 v255, s3, 47
	s_addc_u32 s3, s1, 0
	v_writelane_b32 v255, s3, 49
	s_add_u32 s3, s0, 0x9000000
	v_writelane_b32 v255, s3, 52
	s_addc_u32 s3, s1, 0
	v_writelane_b32 v255, s3, 54
	s_add_u32 s3, s0, 0xf900000
	v_writelane_b32 v255, s3, 50
	s_addc_u32 s3, s1, 0
	v_writelane_b32 v255, s3, 56
	s_lshl_b32 s3, s2, 4
	s_add_i32 s43, s2, 2
	s_add_i32 s48, s2, 4
	s_add_i32 s53, s2, 6
	s_add_i32 s57, s2, 8
	s_add_i32 s41, s3, 16
	s_lshl_b32 s44, s43, 4
	s_add_i32 s46, s3, 48
	s_lshl_b32 s49, s48, 4
	s_add_i32 s51, s3, 0x50
	s_lshl_b32 s54, s53, 4
	s_add_i32 s65, s3, 0x70
	s_lshl_b32 s64, s57, 4
	s_and_b32 s40, s3, 0x70
	s_and_b32 s42, s41, 0x70
	s_and_b32 s45, s44, 0x70
	s_and_b32 s47, s46, 0x70
	s_and_b32 s50, s49, 0x70
	s_and_b32 s52, s51, 0x70
	s_and_b32 s55, s54, 0x70
	s_and_b32 s56, s65, 0x70
	s_and_b32 s58, s64, 0x70
	s_cmp_lt_i32 s2, 8
	s_cselect_b64 s[20:21], -1, 0
	s_cmp_lt_i32 s2, 7
	s_cselect_b64 s[22:23], -1, 0
	s_cmp_lt_i32 s2, 6
	s_cselect_b64 s[24:25], -1, 0
	s_cmp_lt_i32 s2, 5
	s_cselect_b64 s[26:27], -1, 0
	s_cmp_lt_i32 s2, 4
	s_cselect_b64 s[28:29], -1, 0
	s_cmp_lt_i32 s2, 3
	s_cselect_b64 s[30:31], -1, 0
	s_cmp_lt_i32 s2, 2
	s_cselect_b64 s[34:35], -1, 0
	s_cmp_lt_i32 s2, 1
	s_cselect_b64 s[36:37], -1, 0
	s_cmp_lt_i32 s2, 0
	s_cselect_b64 s[38:39], -1, 0
	s_min_i32 s59, s2, 15
	s_min_i32 s2, s2, 14
	s_min_i32 s61, s43, 15
	s_min_i32 s43, s43, 14
	s_min_i32 s67, s48, 15
	s_min_i32 s48, s48, 14
	s_min_i32 s70, s53, 15
	s_min_i32 s53, s53, 14
	s_min_i32 s73, s57, 15
	s_min_i32 s57, s57, 14
	s_lshl_b32 s2, s2, 4
	s_lshl_b32 s43, s43, 4
	s_lshl_b32 s48, s48, 4
	s_lshl_b32 s53, s53, 4
	s_lshl_b32 s57, s57, 4
	v_lshlrev_b32_e32 v8, 3, v3
	v_lshlrev_b32_e32 v10, 4, v3
	v_cmp_eq_u32_e64 s[4:5], 0, v3
	v_or_b32_e32 v3, 1, v7
	s_lshl_b32 s63, s59, 4
	s_add_i32 s2, s2, 16
	s_lshl_b32 s61, s61, 4
	s_add_i32 s43, s43, 16
	s_lshl_b32 s67, s67, 4
	s_add_i32 s48, s48, 16
	s_lshl_b32 s70, s70, 4
	s_add_i32 s53, s53, 16
	s_lshl_b32 s73, s73, 4
	s_add_i32 s57, s57, 16
	v_ashrrev_i32_e32 v65, 3, v0
	v_bfe_u32 v5, v0, 2, 2
	v_and_b32_e32 v6, 7, v0
	v_lshlrev_b32_e32 v0, 3, v0
	v_cmp_lt_u32_e64 s[10:11], v3, v1
	v_or_b32_e32 v3, 2, v7
	s_and_b32 s59, s63, 0x70
	s_and_b32 s60, s2, 0x70
	s_and_b32 s62, s61, 0x70
	s_and_b32 s66, s43, 0x70
	s_and_b32 s68, s67, 0x70
	s_and_b32 s69, s48, 0x70
	s_and_b32 s71, s70, 0x70
	s_and_b32 s72, s53, 0x70
	s_and_b32 s74, s73, 0x70
	s_and_b32 s75, s57, 0x70
	v_lshlrev_b32_e32 v4, 3, v6
	v_lshlrev_b32_e32 v6, 4, v6
	v_mov_b32_e32 v9, v2
	v_and_b32_e32 v0, 24, v0
	v_cmp_lt_u32_e64 s[6:7], v7, v1
	v_cmp_gt_u32_e64 s[8:9], v7, v1
	v_cmp_lt_u32_e64 s[12:13], v3, v1
	v_cmp_gt_u32_e64 s[14:15], v3, v1
	v_or_b32_e32 v3, 3, v7
	v_or_b32_e32 v88, s40, v1
	v_or3_b32 v97, s59, v5, v7
	v_or3_b32 v98, s60, v5, v7
	v_or3_b32 v99, s62, v5, v7
	v_or3_b32 v100, s66, v5, v7
	v_or3_b32 v101, s68, v5, v7
	v_or3_b32 v102, s69, v5, v7
	v_or3_b32 v103, s71, v5, v7
	v_or3_b32 v104, s72, v5, v7
	v_or3_b32 v105, s74, v5, v7
	v_or3_b32 v106, s75, v5, v7
	v_mov_b32_e32 v11, v2
	v_mov_b32_e32 v7, v2
	s_and_b32 s40, s57, 0xffffff80
	v_or_b32_e32 v87, s3, v1
	v_cmp_lt_u32_e64 s[16:17], v3, v1
	v_cmp_gt_u32_e64 s[18:19], v3, v1
	v_or_b32_e32 v89, s42, v1
	v_or_b32_e32 v90, s45, v1
	v_or_b32_e32 v91, s47, v1
	v_or_b32_e32 v92, s50, v1
	v_or_b32_e32 v93, s52, v1
	v_or_b32_e32 v94, s55, v1
	v_or_b32_e32 v95, s56, v1
	v_or_b32_e32 v96, s58, v1
	v_add_u32_e32 v108, 16, v0
	v_lshl_add_u64 v[66:67], s[0:1], 0, v[10:11]
	v_lshl_add_u64 v[68:69], s[0:1], 0, v[6:7]
	s_addk_i32 s40, 0x80
	s_and_b32 s55, s73, 0xffffff80
	s_and_b32 s56, s53, 0xffffff80
	s_and_b32 s57, s70, 0xffffff80
	s_and_b32 s58, s48, 0xffffff80
	s_and_b32 s59, s67, 0xffffff80
	s_and_b32 s60, s43, 0xffffff80
	s_and_b32 s61, s61, 0xffffff80
	s_and_b32 s62, s2, 0xffffff80
	s_and_b32 s63, s63, 0xffffff80
	s_and_b32 s64, s64, 0xffffff80
	s_and_b32 s65, s65, 0xffffff80
	s_and_b32 s66, s54, 0xffffff80
	s_and_b32 s67, s51, 0xffffff80
	s_and_b32 s68, s49, 0xffffff80
	s_and_b32 s69, s46, 0xffffff80
	s_and_b32 s70, s44, 0xffffff80
	s_and_b32 s71, s41, 0xffffff80
	s_and_b32 s72, s3, 0xffffff80
	v_lshl_add_u64 v[0:1], s[0:1], 0, v[8:9]
	s_mov_b64 s[0:1], 0x9900040
	v_add_u32_e32 v86, 0xffffff80, v65
	v_add_u32_e32 v64, 16, v6
	v_add_u32_e32 v107, 16, v10
	v_add_u32_e32 v109, 0xc0, v65
	v_writelane_b32 v255, s40, 62
	s_addk_i32 s55, 0x80
	s_addk_i32 s56, 0x80
	s_addk_i32 s57, 0x80
	s_addk_i32 s58, 0x80
	s_addk_i32 s59, 0x80
	s_addk_i32 s60, 0x80
	s_addk_i32 s61, 0x80
	s_addk_i32 s62, 0x80
	s_addk_i32 s63, 0x80
	s_addk_i32 s64, 0x80
	s_addk_i32 s65, 0x80
	s_addk_i32 s66, 0x80
	s_addk_i32 s67, 0x80
	s_addk_i32 s68, 0x80
	s_addk_i32 s69, 0x80
	s_addk_i32 s70, 0x80
	s_addk_i32 s71, 0x80
	s_addk_i32 s72, 0x80
	v_lshl_add_u64 v[70:71], v[0:1], 0, s[0:1]
	v_lshlrev_b32_e32 v72, 1, v4
	v_lshlrev_b32_e32 v74, 1, v8
	v_mad_u32_u24 v136, v88, s33, v107
	v_mad_u32_u24 v137, v89, s33, v107
	v_mad_u32_u24 v138, v90, s33, v107
	v_mad_u32_u24 v139, v91, s33, v107
	v_mad_u32_u24 v140, v92, s33, v107
	v_mad_u32_u24 v141, v93, s33, v107
	v_mad_u32_u24 v142, v94, s33, v107
	v_mad_u32_u24 v143, v95, s33, v107
	v_mad_u32_u24 v144, v96, s33, v107
	v_mad_u32_u24 v145, v97, s33, v108
	v_mad_u32_u24 v146, v98, s33, v108
	v_mad_u32_u24 v147, v99, s33, v108
	v_mad_u32_u24 v148, v100, s33, v108
	v_mad_u32_u24 v149, v101, s33, v108
	v_mad_u32_u24 v150, v102, s33, v108
	v_mad_u32_u24 v151, v103, s33, v108
	v_mad_u32_u24 v152, v104, s33, v108
	v_and_b32_e32 v135, 64, v223
	v_add_u32_e32 v135, 64, v135
	v_xor_b32_e32 v134, 16, v223
	v_cmp_lt_i32_e32 vcc, v134, v135
	s_nop 1
	v_cndmask_b32_e32 v134, v223, v134, vcc
	v_lshlrev_b32_e32 v134, 2, v134
	v_xor_b32_e32 v0, 32, v223
	v_cmp_lt_i32_e32 vcc, v0, v135
	s_nop 1
	v_cndmask_b32_e32 v135, v223, v0, vcc
	v_lshlrev_b32_e32 v135, 2, v135
	s_mov_b32 s73, s76
	s_mov_b32 s74, s76
	s_branch .LBB0_312

.LBB0_323:
	s_add_i32 s41, s53, s77
	s_and_b32 s41, s41, 0x80
	s_mul_i32 s41, s41, 0x90
	v_add_u32_e32 v0, s41, v136
	ds_read_b128 v[28:31], v0
	ds_read_b128 v[44:47], v0 offset:64
	s_add_i32 s41, s52, s77
	s_and_b32 s41, s41, 0x80
	s_mul_i32 s41, s41, 0x90
	v_add_u32_e32 v1, s41, v137
	ds_read_b128 v[40:43], v1
	s_add_i32 s41, s51, s77
	s_and_b32 s41, s41, 0x80
	s_waitcnt lgkmcnt(2)
	v_mfma_f32_16x16x32_bf16 v[28:31], v[28:31], v[36:39], 0
	s_mul_i32 s41, s41, 0x90
	v_add_u32_e32 v0, s41, v138
	s_add_i32 s41, s50, s77
	s_waitcnt lgkmcnt(1)
	v_mfma_f32_16x16x32_bf16 v[110:113], v[44:47], v[32:35], v[28:31]
	s_and_b32 s41, s41, 0x80
	ds_read_b128 v[44:47], v0 offset:64
	s_nop 0
	ds_read_b128 v[28:31], v1 offset:64
	s_waitcnt lgkmcnt(2)
	v_mfma_f32_16x16x32_bf16 v[40:43], v[40:43], v[36:39], 0
	s_waitcnt lgkmcnt(0)
	v_mfma_f32_16x16x32_bf16 v[28:31], v[28:31], v[32:35], v[40:43]
	s_nop 5
	ds_read_b128 v[40:43], v0
	s_mul_i32 s41, s41, 0x90
	v_add_u32_e32 v0, s41, v139
	s_add_i32 s41, s43, s77
	s_waitcnt lgkmcnt(0)
	v_mfma_f32_16x16x32_bf16 v[40:43], v[40:43], v[36:39], 0
	ds_read_b128 v[48:51], v0 offset:64
	s_and_b32 s41, s41, 0x80
	v_mfma_f32_16x16x32_bf16 v[40:43], v[44:47], v[32:35], v[40:43]
	ds_read_b128 v[44:47], v0
	s_mul_i32 s41, s41, 0x90
	v_add_u32_e32 v0, s41, v140
	s_waitcnt lgkmcnt(0)
	v_mfma_f32_16x16x32_bf16 v[44:47], v[44:47], v[36:39], 0
	ds_read_b128 v[52:55], v0 offset:64
	s_add_i32 s41, s2, s77
	s_and_b32 s41, s41, 0x80
	v_mfma_f32_16x16x32_bf16 v[44:47], v[48:51], v[32:35], v[44:47]
	ds_read_b128 v[48:51], v0
	s_mul_i32 s41, s41, 0x90
	v_add_u32_e32 v0, s41, v141
	s_waitcnt lgkmcnt(0)
	v_mfma_f32_16x16x32_bf16 v[48:51], v[48:51], v[36:39], 0
	ds_read_b128 v[56:59], v0 offset:64
	s_add_i32 s41, s79, s77
	s_and_b32 s41, s41, 0x80
	v_mfma_f32_16x16x32_bf16 v[48:51], v[52:55], v[32:35], v[48:51]
	ds_read_b128 v[52:55], v0
	s_mul_i32 s41, s41, 0x90
	v_add_u32_e32 v0, s41, v142
	s_waitcnt lgkmcnt(0)
	v_mfma_f32_16x16x32_bf16 v[52:55], v[52:55], v[36:39], 0
	ds_read_b128 v[60:63], v0 offset:64
	s_add_i32 s41, s78, s77
	s_and_b32 s41, s41, 0x80
	v_mfma_f32_16x16x32_bf16 v[52:55], v[56:59], v[32:35], v[52:55]
	ds_read_b128 v[56:59], v0
	s_mul_i32 s41, s41, 0x90
	v_add_u32_e32 v0, s41, v143
	s_waitcnt lgkmcnt(0)
	v_mfma_f32_16x16x32_bf16 v[56:59], v[56:59], v[36:39], 0
	ds_read_b128 v[114:117], v0 offset:64
	s_add_i32 s41, s3, s77
	s_and_b32 s41, s41, 0x80
	v_mfma_f32_16x16x32_bf16 v[56:59], v[60:63], v[32:35], v[56:59]
	ds_read_b128 v[60:63], v0
	s_mul_i32 s41, s41, 0x90
	v_add_u32_e32 v0, s41, v144
	s_waitcnt lgkmcnt(0)
	v_mfma_f32_16x16x32_bf16 v[60:63], v[60:63], v[36:39], 0
	s_mov_b32 s41, 0xf149f2ca
	s_cmp_lg_u32 s40, 0
	v_mfma_f32_16x16x32_bf16 v[60:63], v[114:117], v[32:35], v[60:63]
	ds_read_b128 v[114:117], v0
	s_waitcnt lgkmcnt(0)
	v_mfma_f32_16x16x32_bf16 v[36:39], v[114:117], v[36:39], 0
	ds_read_b128 v[114:117], v0 offset:64
	s_waitcnt lgkmcnt(0)
	v_mfma_f32_16x16x32_bf16 v[32:35], v[114:117], v[32:35], v[36:39]
	s_nop 4
	v_mov_b32_e32 v36, s41
	v_mov_b32_e32 v0, s41
	v_mov_b32_e32 v37, s41
	v_cndmask_b32_e64 v3, v32, v36, s[8:9]
	v_cndmask_b32_e64 v0, v110, v0, s[6:7]
	v_cndmask_b32_e64 v1, v111, v37, s[10:11]
	v_cndmask_b32_e64 v36, v3, v32, s[6:7]
	v_cndmask_b32_e64 v33, v37, v33, s[6:7]
	v_cndmask_b32_e64 v32, v112, v37, s[12:13]
	v_cndmask_b32_e64 v34, v34, v37, s[14:15]
	v_cndmask_b32_e64 v3, v113, v37, s[16:17]
	v_cndmask_b32_e64 v35, v35, v37, s[18:19]
	s_cbranch_scc1 .LBB0_325
	v_mov_b32_e32 v37, s41
	v_cndmask_b32_e64 v3, v3, v37, s[20:21]
	v_cndmask_b32_e64 v32, v32, v37, s[20:21]
	v_cndmask_b32_e64 v1, v1, v37, s[20:21]
	v_cndmask_b32_e64 v0, v0, v37, s[20:21]
	v_cndmask_b32_e64 v31, v31, v37, s[22:23]
	v_cndmask_b32_e64 v30, v30, v37, s[22:23]
	v_cndmask_b32_e64 v29, v29, v37, s[22:23]
	v_cndmask_b32_e64 v28, v28, v37, s[22:23]
	v_cndmask_b32_e64 v43, v43, v37, s[24:25]
	v_cndmask_b32_e64 v42, v42, v37, s[24:25]
	v_cndmask_b32_e64 v41, v41, v37, s[24:25]
	v_cndmask_b32_e64 v40, v40, v37, s[24:25]
	v_cndmask_b32_e64 v47, v47, v37, s[26:27]
	v_cndmask_b32_e64 v46, v46, v37, s[26:27]
	v_cndmask_b32_e64 v45, v45, v37, s[26:27]
	v_cndmask_b32_e64 v44, v44, v37, s[26:27]
	v_cndmask_b32_e64 v51, v51, v37, s[28:29]
	v_cndmask_b32_e64 v50, v50, v37, s[28:29]
	v_cndmask_b32_e64 v49, v49, v37, s[28:29]
	v_cndmask_b32_e64 v48, v48, v37, s[28:29]
	v_cndmask_b32_e64 v55, v55, v37, s[30:31]
	v_cndmask_b32_e64 v54, v54, v37, s[30:31]
	v_cndmask_b32_e64 v53, v53, v37, s[30:31]
	v_cndmask_b32_e64 v52, v52, v37, s[30:31]
	v_cndmask_b32_e64 v59, v59, v37, s[34:35]
	v_cndmask_b32_e64 v58, v58, v37, s[34:35]
	v_cndmask_b32_e64 v57, v57, v37, s[34:35]
	v_cndmask_b32_e64 v56, v56, v37, s[34:35]
	v_cndmask_b32_e64 v63, v63, v37, s[36:37]
	v_cndmask_b32_e64 v62, v62, v37, s[36:37]
	v_cndmask_b32_e64 v61, v61, v37, s[36:37]
	v_cndmask_b32_e64 v60, v60, v37, s[36:37]
	v_cndmask_b32_e64 v35, v35, v37, s[38:39]
	v_cndmask_b32_e64 v34, v34, v37, s[38:39]
	v_cndmask_b32_e64 v33, v33, v37, s[38:39]
	v_cndmask_b32_e64 v36, v36, v37, s[38:39]
.LBB0_325:
	v_max3_f32 v37, s41, v0, v1
	v_max3_f32 v38, v3, v32, v28
	v_max3_f32 v37, v37, v29, v30
	v_max3_f32 v38, v38, v31, v40
	v_max3_f32 v37, v37, v41, v42
	v_max3_f32 v38, v38, v43, v44
	v_max3_f32 v37, v37, v45, v46
	v_max3_f32 v38, v38, v47, v48
	v_max3_f32 v37, v37, v49, v50
	v_max3_f32 v38, v38, v51, v52
	v_max3_f32 v37, v37, v53, v54
	v_max3_f32 v38, v38, v55, v56
	v_max3_f32 v37, v37, v57, v58
	v_max3_f32 v38, v38, v59, v60
	v_max3_f32 v37, v37, v61, v62
	v_max3_f32 v38, v38, v63, v36
	v_max3_f32 v37, v37, v33, v34
	v_max3_f32 v37, v37, v38, v35
	s_add_i32 s40, s42, s77
	s_and_b32 s40, s40, 0x80
	ds_bpermute_b32 v38, v134, v37
	s_mov_b32 s81, s80
	s_mov_b32 s82, s80
	s_mov_b32 s83, s80
	s_waitcnt lgkmcnt(0)
	v_max_f32_e32 v38, v38, v38
	v_max_f32_e32 v37, v37, v38
	ds_bpermute_b32 v38, v135, v37
	s_waitcnt lgkmcnt(0)
	v_max_f32_e32 v38, v38, v38
	v_max_f32_e32 v37, v37, v38
	v_sub_f32_e32 v38, v40, v37
	v_exp_f32_e32 v73, v38
	v_sub_f32_e32 v38, v41, v37
	v_exp_f32_e32 v75, v38
	v_sub_f32_e32 v38, v42, v37
	v_exp_f32_e32 v77, v38
	v_sub_f32_e32 v38, v43, v37
	v_exp_f32_e32 v123, v38
	v_sub_f32_e32 v38, v44, v37
	v_exp_f32_e32 v124, v38
	v_sub_f32_e32 v38, v45, v37
	v_exp_f32_e32 v125, v38
	v_sub_f32_e32 v38, v46, v37
	v_exp_f32_e32 v126, v38
	v_sub_f32_e32 v38, v47, v37
	v_exp_f32_e32 v127, v38
	v_sub_f32_e32 v38, v48, v37
	v_exp_f32_e32 v46, v38
	v_sub_f32_e32 v38, v49, v37
	v_sub_f32_e32 v0, v0, v37
	v_sub_f32_e32 v1, v1, v37
	v_exp_f32_e32 v47, v38
	v_sub_f32_e32 v38, v50, v37
	v_exp_f32_e32 v0, v0
	v_exp_f32_e32 v1, v1
	v_exp_f32_e32 v48, v38
	v_sub_f32_e32 v38, v51, v37
	v_exp_f32_e32 v49, v38
	v_sub_f32_e32 v38, v52, v37
	v_exp_f32_e32 v50, v38
	v_sub_f32_e32 v38, v53, v37
	v_exp_f32_e32 v51, v38
	v_sub_f32_e32 v38, v54, v37
	v_cvt_pk_bf16_f32 v54, v0, v1
	v_sub_f32_e32 v0, v32, v37
	v_sub_f32_e32 v1, v3, v37
	v_exp_f32_e32 v0, v0
	v_exp_f32_e32 v1, v1
	v_exp_f32_e32 v52, v38
	v_sub_f32_e32 v38, v55, v37
	v_exp_f32_e32 v53, v38
	v_cvt_pk_bf16_f32 v55, v0, v1
	v_sub_f32_e32 v0, v28, v37
	v_sub_f32_e32 v1, v29, v37
	v_exp_f32_e32 v0, v0
	v_exp_f32_e32 v1, v1
	v_sub_f32_e32 v38, v56, v37
	v_sub_f32_e32 v39, v57, v37
	v_sub_f32_e32 v40, v58, v37
	v_cvt_pk_bf16_f32 v56, v0, v1
	v_sub_f32_e32 v0, v30, v37
	v_sub_f32_e32 v1, v31, v37
	v_exp_f32_e32 v0, v0
	v_exp_f32_e32 v1, v1
	v_sub_f32_e32 v41, v59, v37
	v_sub_f32_e32 v42, v60, v37
	v_sub_f32_e32 v43, v61, v37
	v_cvt_pk_bf16_f32 v57, v0, v1
	s_mul_i32 s40, s40, 0x90
	v_add_u32_e32 v0, s40, v145
	s_add_i32 s40, s45, s77
	s_and_b32 s40, s40, 0x80
	s_mul_i32 s40, s40, 0x90
	v_add_u32_e32 v1, s40, v146
	ds_read_b64_tr_b16 v[30:31], v1 offset:36864
	ds_read_b64_tr_b16 v[60:61], v1 offset:36896
	ds_read_b64_tr_b16 v[28:29], v0 offset:36864
	ds_read_b64_tr_b16 v[58:59], v0 offset:36896
	s_waitcnt lgkmcnt(1)
	v_mfma_f32_16x16x32_bf16 v[110:113], v[28:31], v[54:57], 0
	ds_read_b64_tr_b16 v[28:29], v0 offset:36928
	ds_read_b64_tr_b16 v[30:31], v1 offset:36928
	s_add_i32 s40, s44, s77
	s_and_b32 s40, s40, 0x80
	s_waitcnt lgkmcnt(0)
	v_mfma_f32_16x16x32_bf16 v[114:117], v[28:31], v[54:57], 0
	ds_read_b64_tr_b16 v[28:29], v0 offset:36960
	ds_read_b64_tr_b16 v[30:31], v1 offset:36960
	s_mul_i32 s40, s40, 0x90
	v_add_u32_e32 v0, s40, v147
	s_add_i32 s40, s99, s77
	s_and_b32 s40, s40, 0x80
	s_mul_i32 s40, s40, 0x90
	v_add_u32_e32 v1, s40, v148
	v_cvt_pk_bf16_f32 v124, v124, v125
	v_cvt_pk_bf16_f32 v125, v126, v127
	ds_read_b64_tr_b16 v[128:129], v1 offset:36864
	ds_read_b64_tr_b16 v[132:133], v1 offset:36896
	ds_read_b64_tr_b16 v[126:127], v0 offset:36864
	ds_read_b64_tr_b16 v[130:131], v0 offset:36896
	v_cvt_pk_bf16_f32 v122, v73, v75
	v_cvt_pk_bf16_f32 v123, v77, v123
	s_waitcnt lgkmcnt(4)
	v_mfma_f32_16x16x32_bf16 v[118:121], v[28:31], v[54:57], 0
	v_mov_b64_e32 v[28:29], s[80:81]
	v_mov_b64_e32 v[30:31], s[82:83]
	s_add_i32 s40, s98, s77
	s_waitcnt lgkmcnt(1)
	v_mfma_f32_16x16x32_bf16 v[110:113], v[126:129], v[122:125], v[110:113]
	ds_read_b64_tr_b16 v[126:127], v0 offset:36928
	ds_read_b64_tr_b16 v[128:129], v1 offset:36928
	s_and_b32 s40, s40, 0x80
	v_cvt_pk_bf16_f32 v46, v46, v47
	s_waitcnt lgkmcnt(0)
	v_mfma_f32_16x16x32_bf16 v[114:117], v[126:129], v[122:125], v[114:117]
	ds_read_b64_tr_b16 v[126:127], v0 offset:36960
	ds_read_b64_tr_b16 v[128:129], v1 offset:36960
	s_mul_i32 s40, s40, 0x90
	v_add_u32_e32 v0, s40, v149
	s_add_i32 s40, s97, s77
	v_mfma_f32_16x16x32_bf16 v[58:61], v[58:61], v[54:57], 0
	s_and_b32 s40, s40, 0x80
	s_mul_i32 s40, s40, 0x90
	v_add_u32_e32 v1, s40, v150
	v_mfma_f32_16x16x32_bf16 v[54:57], v[28:31], v[54:57], 0
	v_cvt_pk_bf16_f32 v47, v48, v49
	v_cvt_pk_bf16_f32 v48, v50, v51
	v_cvt_pk_bf16_f32 v49, v52, v53
	v_mfma_f32_16x16x32_bf16 v[58:61], v[130:133], v[122:125], v[58:61]
	s_add_i32 s40, s96, s77
	v_sub_f32_e32 v44, v62, v37
	s_waitcnt lgkmcnt(0)
	v_mfma_f32_16x16x32_bf16 v[118:121], v[126:129], v[122:125], v[118:121]
	v_sub_f32_e32 v45, v63, v37
	s_and_b32 s40, s40, 0x80
	v_exp_f32_e32 v38, v38
	v_mfma_f32_16x16x32_bf16 v[54:57], v[28:31], v[122:125], v[54:57]
	ds_read_b64_tr_b16 v[52:53], v1 offset:36864
	ds_read_b64_tr_b16 v[124:125], v1 offset:36896
	ds_read_b64_tr_b16 v[50:51], v0 offset:36864
	ds_read_b64_tr_b16 v[122:123], v0 offset:36896
	v_exp_f32_e32 v39, v39
	v_exp_f32_e32 v40, v40
	s_waitcnt lgkmcnt(1)
	v_mfma_f32_16x16x32_bf16 v[50:53], v[50:53], v[46:49], v[110:113]
	s_nop 2
	ds_read_b64_tr_b16 v[110:111], v0 offset:36928
	ds_read_b64_tr_b16 v[112:113], v1 offset:36928
	v_exp_f32_e32 v41, v41
	v_exp_f32_e32 v42, v42
	s_waitcnt lgkmcnt(0)
	v_mfma_f32_16x16x32_bf16 v[110:113], v[110:113], v[46:49], v[114:117]
	s_nop 2
	ds_read_b64_tr_b16 v[114:115], v0 offset:36960
	ds_read_b64_tr_b16 v[116:117], v1 offset:36960
	v_exp_f32_e32 v43, v43
	v_exp_f32_e32 v44, v44
	v_exp_f32_e32 v45, v45
	s_mul_i32 s40, s40, 0x90
	v_add_u32_e32 v0, s40, v151
	s_add_i32 s40, s94, s77
	s_and_b32 s40, s40, 0x80
	s_mul_i32 s40, s40, 0x90
	v_add_u32_e32 v1, s40, v152
	v_mfma_f32_16x16x32_bf16 v[58:61], v[122:125], v[46:49], v[58:61]
	v_cvt_pk_bf16_f32 v38, v38, v39
	v_cvt_pk_bf16_f32 v39, v40, v41
	v_cvt_pk_bf16_f32 v40, v42, v43
	s_waitcnt lgkmcnt(0)
	v_mfma_f32_16x16x32_bf16 v[114:117], v[114:117], v[46:49], v[118:121]
	v_cvt_pk_bf16_f32 v41, v44, v45
	v_sub_f32_e32 v36, v36, v37
	v_mfma_f32_16x16x32_bf16 v[46:49], v[28:31], v[46:49], v[54:57]
	ds_read_b64_tr_b16 v[44:45], v1 offset:36864
	s_nop 1
	ds_read_b64_tr_b16 v[56:57], v1 offset:36896
	ds_read_b64_tr_b16 v[42:43], v0 offset:36864
	ds_read_b64_tr_b16 v[54:55], v0 offset:36896
	v_sub_f32_e32 v33, v33, v37
	v_exp_f32_e32 v36, v36
	v_exp_f32_e32 v33, v33
	s_add_i32 s40, s93, s77
	v_sub_f32_e32 v34, v34, v37
	v_sub_f32_e32 v35, v35, v37
	s_waitcnt lgkmcnt(1)
	v_mfma_f32_16x16x32_bf16 v[42:45], v[42:45], v[38:41], v[50:53]
	s_and_b32 s40, s40, 0x80
	v_exp_f32_e32 v34, v34
	v_exp_f32_e32 v35, v35
	s_waitcnt lgkmcnt(0)
	v_mfma_f32_16x16x32_bf16 v[50:53], v[54:57], v[38:41], v[58:61]
	ds_read_b64_tr_b16 v[54:55], v0 offset:36928
	ds_read_b64_tr_b16 v[56:57], v1 offset:36928
	s_nop 0
	ds_read_b64_tr_b16 v[58:59], v0 offset:36960
	ds_read_b64_tr_b16 v[60:61], v1 offset:36960
	v_or_b32_e32 v32, s40, v105
	s_add_i32 s40, s92, s77
	s_and_b32 s40, s40, 0x80
	v_cvt_pk_bf16_f32 v0, v36, v33
	v_or_b32_e32 v33, s40, v106
	v_mad_u32_u24 v62, v33, s33, v108
	s_waitcnt lgkmcnt(2)
	v_mfma_f32_16x16x32_bf16 v[54:57], v[54:57], v[38:41], v[110:113]
	v_cvt_pk_bf16_f32 v1, v34, v35
	v_mad_u32_u24 v36, v32, s33, v108
	v_mov_b32_e32 v3, v2
	s_waitcnt lgkmcnt(0)
	v_mfma_f32_16x16x32_bf16 v[58:61], v[58:61], v[38:41], v[114:117]
	v_mfma_f32_16x16x32_bf16 v[38:41], v[28:31], v[38:41], v[46:49]
	ds_read_b64_tr_b16 v[34:35], v62 offset:36864
	s_nop 1
	ds_read_b64_tr_b16 v[48:49], v62 offset:36896
	ds_read_b64_tr_b16 v[32:33], v36 offset:36864
	ds_read_b64_tr_b16 v[46:47], v36 offset:36896
	s_waitcnt lgkmcnt(1)
	v_mfma_f32_16x16x32_bf16 v[32:35], v[32:35], v[0:3], v[42:45]
	s_waitcnt lgkmcnt(0)
	v_mfma_f32_16x16x32_bf16 v[42:45], v[46:49], v[0:3], v[50:53]
	ds_read_b64_tr_b16 v[46:47], v36 offset:36928
	ds_read_b64_tr_b16 v[48:49], v62 offset:36928
	s_nop 0
	ds_read_b64_tr_b16 v[50:51], v36 offset:36960
	ds_read_b64_tr_b16 v[52:53], v62 offset:36960
	v_mfma_f32_16x16x32_bf16 v[28:31], v[28:31], v[0:3], v[38:41]
	s_waitcnt lgkmcnt(2)
	v_mfma_f32_16x16x32_bf16 v[46:49], v[46:49], v[0:3], v[54:57]
	s_waitcnt lgkmcnt(0)
	v_mfma_f32_16x16x32_bf16 v[50:53], v[50:53], v[0:3], v[58:61]
	s_nop 3
	v_div_scale_f32 v0, s[40:41], v28, v28, 1.0
	v_rcp_f32_e32 v1, v0
	s_nop 0
	v_fma_f32 v3, -v0, v1, 1.0
	v_fmac_f32_e32 v1, v3, v1
	v_div_scale_f32 v3, vcc, 1.0, v28, 1.0
	v_mul_f32_e32 v29, v3, v1
	v_fma_f32 v30, -v0, v29, v3
	v_fmac_f32_e32 v29, v30, v1
	v_fma_f32 v0, -v0, v29, v3
	v_div_fmas_f32 v0, v0, v1, v29
	v_div_fixup_f32 v0, v0, v28, 1.0
	v_pk_mul_f32 v[34:35], v[34:35], v[0:1] op_sel_hi:[1,0]
	v_pk_mul_f32 v[32:33], v[32:33], v[0:1] op_sel_hi:[1,0]
	v_lshl_add_u64 v[30:31], v[84:85], 0, s[46:47]
	v_cvt_pk_bf16_f32 v32, v32, v33
	v_cvt_pk_bf16_f32 v33, v34, v35
	global_store_dwordx2 v[30:31], v[32:33], off offset:-64
	v_pk_mul_f32 v[32:33], v[44:45], v[0:1] op_sel_hi:[1,0]
	v_pk_mul_f32 v[34:35], v[42:43], v[0:1] op_sel_hi:[1,0]
	s_nop 0
	v_cvt_pk_bf16_f32 v34, v34, v35
	v_cvt_pk_bf16_f32 v35, v32, v33
	global_store_dwordx2 v[30:31], v[34:35], off offset:-32
	v_pk_mul_f32 v[32:33], v[48:49], v[0:1] op_sel_hi:[1,0]
	v_pk_mul_f32 v[34:35], v[46:47], v[0:1] op_sel_hi:[1,0]
	s_nop 0
	v_cvt_pk_bf16_f32 v34, v34, v35
	v_cvt_pk_bf16_f32 v35, v32, v33
	v_pk_mul_f32 v[32:33], v[52:53], v[0:1] op_sel_hi:[1,0]
	v_pk_mul_f32 v[0:1], v[50:51], v[0:1] op_sel_hi:[1,0]
	global_store_dwordx2 v[30:31], v[34:35], off
	v_cvt_pk_bf16_f32 v0, v0, v1
	v_cvt_pk_bf16_f32 v1, v32, v33
	global_store_dwordx2 v[30:31], v[0:1], off offset:32
	s_and_saveexec_b64 s[48:49], s[4:5]
	s_cbranch_execz .LBB0_320
	s_mov_b32 s40, 0x800000
	v_cmp_gt_f32_e32 vcc, s40, v28
	s_mov_b32 s40, 0x3f317217
	v_add_u32_e32 v0, s77, v76
	v_cndmask_b32_e64 v1, 0, 32, vcc
	v_ldexp_f32 v1, v28, v1
	v_log_f32_e32 v3, v1
	v_lshlrev_b32_e32 v0, s76, v0
	v_add_u32_e32 v0, s75, v0
	v_ashrrev_i32_e32 v1, 31, v0
	v_mul_f32_e32 v28, 0x3f317217, v3
	v_fma_f32 v28, v3, s40, -v28
	v_fmac_f32_e32 v28, 0x3377d1cf, v3
	s_mov_b32 s40, 0x7f800000
	v_fmac_f32_e32 v28, 0x3f317217, v3
	v_cmp_lt_f32_e64 s[40:41], |v3|, s40
	v_lshlrev_b64 v[0:1], 6, v[0:1]
	v_lshl_add_u64 v[0:1], s[0:1], 0, v[0:1]
	v_cndmask_b32_e64 v3, v3, v28, s[40:41]
	v_mov_b32_e32 v28, 0x41b17218
	v_cndmask_b32_e32 v28, 0, v28, vcc
	v_sub_f32_e32 v3, v3, v28
	v_fmac_f32_e32 v3, 0x3f317218, v37
	global_store_dword v[0:1], v3, off
	s_branch .LBB0_320
